# grid barrier: every workgroup spins on the global release generation (TOPGEN) instead of a per-XCD release word re-published by the XCD leader; leader no longer issues the per-XCD release atomic (-0.5
# speedup vs baseline: 1.0110x; 1.0060x over previous
.LBB0_879:
	s_or_b64 exec, exec, s[4:5]
	v_cvt_f32_u32_e32 v4, v2
	s_waitcnt vmcnt(0)
	v_readfirstlane_b32 s4, v3
	v_sub_u32_e32 v3, 0, v2
	v_rcp_iflag_f32_e32 v4, v4
	v_add_u32_e32 v5, s4, v1
	v_mul_f32_e32 v4, 0x4f7ffffe, v4
	v_cvt_u32_f32_e32 v4, v4
	v_mul_lo_u32 v1, v3, v4
	v_mul_hi_u32 v1, v4, v1
	v_add_u32_e32 v1, v4, v1
	v_mul_hi_u32 v1, v5, v1
	v_mul_lo_u32 v3, v1, v2
	v_sub_u32_e32 v3, v5, v3
	v_add_u32_e32 v4, 1, v1
	v_cmp_ge_u32_e32 vcc, v3, v2
	s_nop 1
	v_cndmask_b32_e32 v1, v1, v4, vcc
	v_sub_u32_e32 v4, v3, v2
	v_cndmask_b32_e32 v3, v3, v4, vcc
	v_add_u32_e32 v4, 1, v1
	v_cmp_ge_u32_e32 vcc, v3, v2
	v_add_u32_e32 v3, 1, v5
	s_nop 0
	v_cndmask_b32_e32 v1, v1, v4, vcc
	v_mul_lo_u32 v4, v2, v1
	v_add_u32_e32 v2, v4, v2
	v_cmp_ne_u32_e32 vcc, v3, v2
	s_and_saveexec_b64 s[4:5], vcc
	s_xor_b64 s[4:5], exec, s[4:5]
	s_cbranch_execz .LBB0_893
	v_readlane_b32 s12, v254, 14
	v_readlane_b32 s13, v254, 15
	s_waitcnt lgkmcnt(0)
	s_nop 3
	global_load_dword v0, v145, s[12:13] sc1
	s_waitcnt vmcnt(0)
	v_cmp_eq_u32_e32 vcc, v0, v1
	s_and_saveexec_b64 s[12:13], vcc
	s_cbranch_execz .LBB0_892
	s_mov_b32 s15, 1
	s_mov_b64 s[16:17], 0
	s_branch .LBB0_883

.LBB0_887:
	v_readlane_b32 s26, v254, 14
	v_readlane_b32 s27, v254, 15
	s_add_i32 s15, s15, 1
	s_mov_b64 s[36:37], -1
	s_nop 2
	global_load_dword v0, v145, s[26:27] sc1
	s_waitcnt vmcnt(0)
	v_cmp_ne_u32_e32 vcc, v0, v1
	s_orn2_b64 s[26:27], vcc, exec
	s_branch .LBB0_882

.LBB0_910:
	s_or_b64 exec, exec, s[4:5]
	s_mov_b64 s[4:5], exec
	v_mbcnt_lo_u32_b32 v0, s4, 0
	v_mbcnt_hi_u32_b32 v0, s5, v0
	v_cmp_eq_u32_e32 vcc, 0, v0
	s_waitcnt vmcnt(0)
	buffer_inv sc1
	s_and_saveexec_b64 s[12:13], vcc
	s_cbranch_execz .LBB0_912
	s_bcnt1_i32_b64 s4, s[4:5]
	v_mov_b32_e32 v0, s4
	v_readlane_b32 s4, v254, 10
	v_readlane_b32 s5, v254, 11
	s_nop 4
.LBB0_912:
	s_or_b64 exec, exec, s[12:13]
	s_waitcnt vmcnt(0)
